# attention K staging: 8-lane sum of squares via DPP adds (no ds_bpermute round trips); kg gain vector loaded once per unit
# baseline (speedup 1.0000x reference)
; __device__ __forceinline__ void attn_phase(LAS unsigned char* lds, const Args& a, int j, int bid, int G, int tid) {
;     ...
;         const int start = qb * 128 - 128;
;         {
;             const bf16_t* vb = VTg + seq_off_ch(seq) / 4 + (size_t)(hk * 64) * seq_LS(seq) + XPAD;
;             const int LS = seq_LS(seq);
;             u32x4 kraw[7], vraw[7];
; #pragma unroll
;             for (int it = 0; it < 7; ++it) {
;                 const int idx = it * 512 + tid;
;                 { const int slot = idx >> 3, dc = idx & 7; const int pos = slot < 16 ? slot : start + slot - 16;
;                   const bool valid = (idx < 416 * 8) && (slot < 16 || (slot < 400 && pos >= 16 && pos < L));
;                   kraw[it] = (u32x4){0u, 0u, 0u, 0u};
;                   if (valid) kraw[it] = *(const u32x4*)(QK + (size_t)seq_row(seq, pos) * 1280 + 1024 + hk * 64 + dc * 8); }
;                 { const int d = idx / 52, c8 = idx % 52; const int pos0 = c8 < 2 ? 8 * c8 : start + 8 * c8 - 16;
;                   const bool valid = (idx < 64 * 52) && (c8 < 2 || (c8 < 50 && pos0 >= 16 && pos0 < L));
;                   vraw[it] = (u32x4){0u, 0u, 0u, 0u};
;                   if (valid) vraw[it] = *(const u32x4*)(vb + (size_t)d * LS + pos0); }
;     ...
;                 const f32x4 g0 = *(const f32x4*)(kg + dc * 8), g1 = *(const f32x4*)(kg + dc * 8 + 4);
.LBB0_668:
	s_lshl_b32 s58, s25, 7
	s_add_i32 s25, s58, 0xffffff70
	v_mov_b32_e32 v1, s25
	s_and_b32 s22, s85, 3
	s_lshl_b32 s28, s27, 12
	v_cndmask_b32_e64 v1, v1, 0, s[90:91]
	s_lshl_b32 s26, s22, 6
	s_lshl_b32 s23, s27, 13
	s_addk_i32 s28, 0x4000
	v_add_u32_e32 v2, v1, v179
	s_and_b64 s[18:19], s[18:19], exec
	v_cmp_lt_i32_e32 vcc, 15, v2
	s_cselect_b32 s23, s23, s28
	s_and_b64 s[18:19], s[96:97], vcc
	v_cmp_gt_i32_e32 vcc, s47, v2
	s_and_b64 s[18:19], s[18:19], vcc
	v_cndmask_b32_e64 v3, 0, 1, s[18:19]
	v_cndmask_b32_e64 v1, 0, 1, s[10:11]
	v_cndmask_b32_e64 v3, v3, v1, s[92:93]
	s_lshl_b32 s51, s27, 4
	v_and_b32_e32 v3, 1, v3
	s_add_i32 s50, s23, -16
	s_add_i32 s51, s51, 0x18000
	global_load_dwordx4 v[100:103], v[160:161], off offset:16
	global_load_dwordx4 v[104:107], v[160:161], off
	v_mov_b32_e32 v0, 0
	v_cmp_eq_u32_e32 vcc, 1, v3
	v_lshlrev_b32_e32 v32, 1, v158
	v_mov_b32_e32 v16, 0
	v_mov_b32_e32 v17, 0
	v_mov_b32_e32 v18, 0
	v_mov_b32_e32 v19, 0
	s_and_saveexec_b64 s[18:19], vcc
	s_cbranch_execz .LBB0_670
	v_mov_b32_e32 v3, s50
	v_mov_b32_e32 v4, s51
	v_cmp_gt_i32_e32 vcc, 16, v2
	s_movk_i32 s27, 0xa00
	s_lshl_b32 s56, s26, 1
	v_cndmask_b32_e32 v3, v3, v4, vcc
	v_add_u32_e32 v4, v3, v2
	v_mov_b64_e32 v[2:3], s[20:21]
	v_mad_i64_i32 v[2:3], s[28:29], v4, s27, v[2:3]
	v_lshl_add_u64 v[2:3], v[2:3], 0, s[56:57]
	v_lshl_add_u64 v[2:3], v[2:3], 0, v[32:33]
	global_load_dwordx4 v[16:19], v[2:3], off offset:2048

; #define LAS __attribute__((address_space(3)))
; __device__ __forceinline__ unsigned cvtpk(float lo, float hi) { f32x2 v = {lo, hi}; bf16x2_t b = __builtin_convertvector(v, bf16x2_t); return __builtin_bit_cast(unsigned, b); }
; __device__ __forceinline__ void attn_phase(LAS unsigned char* lds, const Args& a, int j, int bid, int G, int tid) {
;     ...
;             for (int it = 0; it < 7; ++it) {
;                 const int idx = it * 512 + tid;
;                 const int slot = idx >> 3, dc = idx & 7;
;                 const u32x4 raw = kraw[it];
;                 float x[8] = {bflo(raw.x), bfhi(raw.x), bflo(raw.y), bfhi(raw.y), bflo(raw.z), bfhi(raw.z), bflo(raw.w), bfhi(raw.w)};
;                 float ss = 0.f;
; #pragma unroll
;                 for (int i = 0; i < 8; ++i) ss += x[i] * x[i];
;                 ss += __shfl_xor(ss, 1); ss += __shfl_xor(ss, 2); ss += __shfl_xor(ss, 4);
;                 const float ri = __builtin_amdgcn_rsqf(ss * (1.0f / 64.0f) + EPS);
;                 const f32x4 g0 = *(const f32x4*)(kg + dc * 8), g1 = *(const f32x4*)(kg + dc * 8 + 4);
;                 u32x4 o; o.x = cvtpk(x[0] * ri * g0[0], x[1] * ri * g0[1]); o.y = cvtpk(x[2] * ri * g0[2], x[3] * ri * g0[3]);
;                 o.z = cvtpk(x[4] * ri * g1[0], x[5] * ri * g1[1]); o.w = cvtpk(x[6] * ri * g1[2], x[7] * ri * g1[3]);
;                 if (idx < 416 * 8) *(LAS u32x4*)(lds + KN_OFF + slot * KSTR + dc * 16) = o;
;                 const int d = idx / 52, c8 = idx % 52;
;                 if (idx < 64 * 52) *(LAS u32x4*)(lds + VT_OFF + d * VSTR + c8 * 16) = vraw[it];
;             }
.LBB0_696:
	s_or_b64 exec, exec, s[6:7]
	s_waitcnt vmcnt(0)
	v_lshlrev_b32_e32 v58, 16, v16
	v_and_b32_e32 v59, 0xffff0000, v16
	v_lshlrev_b32_e32 v16, 16, v17
	v_and_b32_e32 v17, 0xffff0000, v17
	v_pk_mul_f32 v[62:63], v[58:59], v[58:59]
	v_pk_mul_f32 v[64:65], v[16:17], v[16:17]
	v_add_f32_e32 v32, v62, v63
	v_lshlrev_b32_e32 v60, 16, v18
	v_and_b32_e32 v61, 0xffff0000, v18
	v_add_f32_e32 v32, v64, v32
	v_pk_mul_f32 v[66:67], v[60:61], v[60:61]
	v_add_f32_e32 v32, v65, v32
	v_lshlrev_b32_e32 v18, 16, v19
	v_and_b32_e32 v19, 0xffff0000, v19
	v_add_f32_e32 v32, v66, v32
	v_pk_mul_f32 v[68:69], v[18:19], v[18:19]
	v_add_f32_e32 v32, v67, v32
	v_add_f32_e32 v32, v68, v32
	v_add_f32_e32 v32, v69, v32
	s_nop 1
	v_add_f32_dpp v32, v32, v32 quad_perm:[1,0,3,2] row_mask:0xf bank_mask:0xf
	s_nop 1
	v_add_f32_dpp v32, v32, v32 quad_perm:[2,3,0,1] row_mask:0xf bank_mask:0xf
	s_nop 1
	v_add_f32_dpp v32, v32, v32 row_half_mirror row_mask:0xf bank_mask:0xf
	s_and_saveexec_b64 s[6:7], s[10:11]
	s_cbranch_execz .LBB0_698
	v_fmamk_f32 v32, v32, 0x3c800000, v203
	v_rsq_f32_e32 v32, v32
	s_nop 0
	v_pk_mul_f32 v[18:19], v[32:33], v[18:19] op_sel_hi:[0,1]
	v_pk_mul_f32 v[60:61], v[32:33], v[60:61] op_sel_hi:[0,1]
	v_pk_mul_f32 v[16:17], v[32:33], v[16:17] op_sel_hi:[0,1]
	v_pk_mul_f32 v[58:59], v[32:33], v[58:59] op_sel_hi:[0,1]
	v_pk_mul_f32 v[18:19], v[18:19], v[102:103]
	v_pk_mul_f32 v[60:61], v[60:61], v[100:101]
	v_pk_mul_f32 v[16:17], v[16:17], v[106:107]
	v_pk_mul_f32 v[58:59], v[58:59], v[104:105]
	v_cvt_pk_bf16_f32 v19, v18, v19
	v_cvt_pk_bf16_f32 v18, v60, v61
	v_cvt_pk_bf16_f32 v17, v16, v17
	v_cvt_pk_bf16_f32 v16, v58, v59
	ds_write_b128 v201, v[16:19]
	ds_write_b128 v215, v[0:3] offset:59904
.LBB0_698:
	s_or_b64 exec, exec, s[6:7]
	v_lshlrev_b32_e32 v0, 16, v24
	v_and_b32_e32 v1, 0xffff0000, v24
	v_lshlrev_b32_e32 v2, 16, v25
	v_and_b32_e32 v3, 0xffff0000, v25
	v_pk_mul_f32 v[24:25], v[0:1], v[0:1]
	v_lshlrev_b32_e32 v16, 16, v26
	v_and_b32_e32 v17, 0xffff0000, v26
	v_lshlrev_b32_e32 v18, 16, v27
	v_and_b32_e32 v19, 0xffff0000, v27
	v_pk_mul_f32 v[26:27], v[2:3], v[2:3]
	v_add_f32_e32 v24, v24, v25
	v_add_f32_e32 v24, v26, v24
	v_pk_mul_f32 v[58:59], v[16:17], v[16:17]
	v_add_f32_e32 v24, v27, v24
	v_add_f32_e32 v24, v58, v24
	v_pk_mul_f32 v[60:61], v[18:19], v[18:19]
	v_add_f32_e32 v24, v59, v24
	v_add_f32_e32 v24, v60, v24
	v_add_f32_e32 v24, v61, v24
	s_nop 1
	v_add_f32_dpp v24, v24, v24 quad_perm:[1,0,3,2] row_mask:0xf bank_mask:0xf
	s_nop 1
	v_add_f32_dpp v24, v24, v24 quad_perm:[2,3,0,1] row_mask:0xf bank_mask:0xf
	s_nop 1
	v_add_f32_dpp v24, v24, v24 row_half_mirror row_mask:0xf bank_mask:0xf
	s_and_saveexec_b64 s[6:7], s[70:71]
	s_cbranch_execz .LBB0_700
	v_fmamk_f32 v24, v24, 0x3c800000, v203
	v_rsq_f32_e32 v24, v24
	s_nop 0
	v_pk_mul_f32 v[18:19], v[24:25], v[18:19] op_sel_hi:[0,1]
	v_pk_mul_f32 v[16:17], v[24:25], v[16:17] op_sel_hi:[0,1]
	v_pk_mul_f32 v[2:3], v[24:25], v[2:3] op_sel_hi:[0,1]
	v_pk_mul_f32 v[0:1], v[24:25], v[0:1] op_sel_hi:[0,1]
	v_pk_mul_f32 v[18:19], v[18:19], v[102:103]
	v_pk_mul_f32 v[16:17], v[16:17], v[100:101]
	v_pk_mul_f32 v[24:25], v[2:3], v[106:107]
	v_pk_mul_f32 v[26:27], v[0:1], v[104:105]
	v_cvt_pk_bf16_f32 v3, v18, v19
	v_cvt_pk_bf16_f32 v2, v16, v17
	v_cvt_pk_bf16_f32 v1, v24, v25
	v_cvt_pk_bf16_f32 v0, v26, v27
	ds_write_b128 v216, v[0:3]
	ds_write_b128 v217, v[4:7] offset:59904
.LBB0_700:
	s_or_b64 exec, exec, s[6:7]
	v_lshlrev_b32_e32 v0, 16, v34
	v_and_b32_e32 v1, 0xffff0000, v34
	v_lshlrev_b32_e32 v2, 16, v35
	v_and_b32_e32 v3, 0xffff0000, v35
	v_pk_mul_f32 v[16:17], v[0:1], v[0:1]
	v_pk_mul_f32 v[18:19], v[2:3], v[2:3]
	v_add_f32_e32 v16, v16, v17
	v_lshlrev_b32_e32 v4, 16, v36
	v_and_b32_e32 v5, 0xffff0000, v36
	v_add_f32_e32 v16, v18, v16
	s_waitcnt lgkmcnt(0)
	v_pk_mul_f32 v[24:25], v[4:5], v[4:5]
	v_add_f32_e32 v16, v19, v16
	v_lshlrev_b32_e32 v6, 16, v37
	v_and_b32_e32 v7, 0xffff0000, v37
	v_add_f32_e32 v16, v24, v16
	v_pk_mul_f32 v[26:27], v[6:7], v[6:7]
	v_add_f32_e32 v16, v25, v16
	v_add_f32_e32 v16, v26, v16
	v_add_f32_e32 v16, v27, v16
	s_nop 1
	v_add_f32_dpp v16, v16, v16 quad_perm:[1,0,3,2] row_mask:0xf bank_mask:0xf
	s_nop 1
	v_add_f32_dpp v16, v16, v16 quad_perm:[2,3,0,1] row_mask:0xf bank_mask:0xf
	s_nop 1
	v_add_f32_dpp v16, v16, v16 row_half_mirror row_mask:0xf bank_mask:0xf
	s_and_saveexec_b64 s[6:7], s[76:77]
	s_cbranch_execz .LBB0_702
	v_fmamk_f32 v16, v16, 0x3c800000, v203
	v_rsq_f32_e32 v16, v16
	s_nop 0
	v_pk_mul_f32 v[6:7], v[16:17], v[6:7] op_sel_hi:[0,1]
	v_pk_mul_f32 v[4:5], v[16:17], v[4:5] op_sel_hi:[0,1]
	v_pk_mul_f32 v[2:3], v[16:17], v[2:3] op_sel_hi:[0,1]
	v_pk_mul_f32 v[0:1], v[16:17], v[0:1] op_sel_hi:[0,1]
	v_pk_mul_f32 v[6:7], v[6:7], v[102:103]
	v_pk_mul_f32 v[4:5], v[4:5], v[100:101]
	v_pk_mul_f32 v[16:17], v[2:3], v[106:107]
	v_pk_mul_f32 v[18:19], v[0:1], v[104:105]
	v_cvt_pk_bf16_f32 v3, v6, v7
	v_cvt_pk_bf16_f32 v2, v4, v5
	v_cvt_pk_bf16_f32 v1, v16, v17
	v_cvt_pk_bf16_f32 v0, v18, v19
	ds_write_b128 v218, v[0:3]
	ds_write_b128 v219, v[8:11] offset:59904
; #define LAS __attribute__((address_space(3)))
; __device__ __forceinline__ unsigned cvtpk(float lo, float hi) { f32x2 v = {lo, hi}; bf16x2_t b = __builtin_convertvector(v, bf16x2_t); return __builtin_bit_cast(unsigned, b); }
; __device__ __forceinline__ void attn_phase(LAS unsigned char* lds, const Args& a, int j, int bid, int G, int tid) {
;     ...
;             for (int it = 0; it < 7; ++it) {
;                 const int idx = it * 512 + tid;
;                 const int slot = idx >> 3, dc = idx & 7;
;                 const u32x4 raw = kraw[it];
;                 float x[8] = {bflo(raw.x), bfhi(raw.x), bflo(raw.y), bfhi(raw.y), bflo(raw.z), bfhi(raw.z), bflo(raw.w), bfhi(raw.w)};
;                 float ss = 0.f;
; #pragma unroll
;                 for (int i = 0; i < 8; ++i) ss += x[i] * x[i];
;                 ss += __shfl_xor(ss, 1); ss += __shfl_xor(ss, 2); ss += __shfl_xor(ss, 4);
;                 const float ri = __builtin_amdgcn_rsqf(ss * (1.0f / 64.0f) + EPS);
;                 const f32x4 g0 = *(const f32x4*)(kg + dc * 8), g1 = *(const f32x4*)(kg + dc * 8 + 4);
;                 u32x4 o; o.x = cvtpk(x[0] * ri * g0[0], x[1] * ri * g0[1]); o.y = cvtpk(x[2] * ri * g0[2], x[3] * ri * g0[3]);
;                 o.z = cvtpk(x[4] * ri * g1[0], x[5] * ri * g1[1]); o.w = cvtpk(x[6] * ri * g1[2], x[7] * ri * g1[3]);
;                 if (idx < 416 * 8) *(LAS u32x4*)(lds + KN_OFF + slot * KSTR + dc * 16) = o;
;                 const int d = idx / 52, c8 = idx % 52;
;                 if (idx < 64 * 52) *(LAS u32x4*)(lds + VT_OFF + d * VSTR + c8 * 16) = vraw[it];
;             }
.LBB0_702:
	s_or_b64 exec, exec, s[6:7]
	v_lshlrev_b32_e32 v0, 16, v42
	v_and_b32_e32 v1, 0xffff0000, v42
	v_lshlrev_b32_e32 v2, 16, v43
	v_and_b32_e32 v3, 0xffff0000, v43
	v_pk_mul_f32 v[8:9], v[0:1], v[0:1]
	v_pk_mul_f32 v[10:11], v[2:3], v[2:3]
	v_add_f32_e32 v8, v8, v9
	v_lshlrev_b32_e32 v4, 16, v44
	v_and_b32_e32 v5, 0xffff0000, v44
	v_add_f32_e32 v8, v10, v8
	s_waitcnt lgkmcnt(0)
	v_pk_mul_f32 v[16:17], v[4:5], v[4:5]
	v_add_f32_e32 v8, v11, v8
	v_lshlrev_b32_e32 v6, 16, v45
	v_and_b32_e32 v7, 0xffff0000, v45
	v_add_f32_e32 v8, v16, v8
	v_pk_mul_f32 v[18:19], v[6:7], v[6:7]
	v_add_f32_e32 v8, v17, v8
	v_add_f32_e32 v8, v18, v8
	v_add_f32_e32 v8, v19, v8
	s_nop 1
	v_add_f32_dpp v8, v8, v8 quad_perm:[1,0,3,2] row_mask:0xf bank_mask:0xf
	s_nop 1
	v_add_f32_dpp v8, v8, v8 quad_perm:[2,3,0,1] row_mask:0xf bank_mask:0xf
	s_nop 1
	v_add_f32_dpp v8, v8, v8 row_half_mirror row_mask:0xf bank_mask:0xf
	s_and_saveexec_b64 s[6:7], s[82:83]
	s_cbranch_execz .LBB0_704
	v_fmamk_f32 v8, v8, 0x3c800000, v203
	v_rsq_f32_e32 v8, v8
	s_nop 0
	v_pk_mul_f32 v[6:7], v[8:9], v[6:7] op_sel_hi:[0,1]
	v_pk_mul_f32 v[4:5], v[8:9], v[4:5] op_sel_hi:[0,1]
	v_pk_mul_f32 v[2:3], v[8:9], v[2:3] op_sel_hi:[0,1]
	v_pk_mul_f32 v[0:1], v[8:9], v[0:1] op_sel_hi:[0,1]
	v_pk_mul_f32 v[6:7], v[6:7], v[102:103]
	v_pk_mul_f32 v[4:5], v[4:5], v[100:101]
	v_pk_mul_f32 v[8:9], v[2:3], v[106:107]
	v_pk_mul_f32 v[10:11], v[0:1], v[104:105]
	v_cvt_pk_bf16_f32 v3, v6, v7
	v_cvt_pk_bf16_f32 v2, v4, v5
	v_cvt_pk_bf16_f32 v1, v8, v9
	v_cvt_pk_bf16_f32 v0, v10, v11
	ds_write_b128 v220, v[0:3]
	ds_write_b128 v221, v[12:15] offset:59904
.LBB0_704:
	s_or_b64 exec, exec, s[6:7]
	v_lshlrev_b32_e32 v0, 16, v46
	v_and_b32_e32 v1, 0xffff0000, v46
	v_lshlrev_b32_e32 v2, 16, v47
	v_and_b32_e32 v3, 0xffff0000, v47
	s_waitcnt lgkmcnt(0)
	v_pk_mul_f32 v[8:9], v[0:1], v[0:1]
	v_pk_mul_f32 v[10:11], v[2:3], v[2:3]
	v_add_f32_e32 v8, v8, v9
	v_lshlrev_b32_e32 v4, 16, v48
	v_and_b32_e32 v5, 0xffff0000, v48
	v_add_f32_e32 v8, v10, v8
	v_pk_mul_f32 v[12:13], v[4:5], v[4:5]
	v_add_f32_e32 v8, v11, v8
	v_lshlrev_b32_e32 v6, 16, v49
	v_and_b32_e32 v7, 0xffff0000, v49
	v_add_f32_e32 v8, v12, v8
	v_pk_mul_f32 v[14:15], v[6:7], v[6:7]
	v_add_f32_e32 v8, v13, v8
	v_add_f32_e32 v8, v14, v8
	v_add_f32_e32 v8, v15, v8
	s_nop 1
	v_add_f32_dpp v8, v8, v8 quad_perm:[1,0,3,2] row_mask:0xf bank_mask:0xf
	s_nop 1
	v_add_f32_dpp v8, v8, v8 quad_perm:[2,3,0,1] row_mask:0xf bank_mask:0xf
	s_nop 1
	v_add_f32_dpp v8, v8, v8 row_half_mirror row_mask:0xf bank_mask:0xf
	s_and_saveexec_b64 s[6:7], s[88:89]
	s_cbranch_execz .LBB0_706
	v_fmamk_f32 v8, v8, 0x3c800000, v203
	v_rsq_f32_e32 v8, v8
	s_nop 0
	v_pk_mul_f32 v[6:7], v[8:9], v[6:7] op_sel_hi:[0,1]
	v_pk_mul_f32 v[4:5], v[8:9], v[4:5] op_sel_hi:[0,1]
	v_pk_mul_f32 v[2:3], v[8:9], v[2:3] op_sel_hi:[0,1]
	v_pk_mul_f32 v[0:1], v[8:9], v[0:1] op_sel_hi:[0,1]
	v_pk_mul_f32 v[6:7], v[6:7], v[102:103]
	v_pk_mul_f32 v[4:5], v[4:5], v[100:101]
	v_pk_mul_f32 v[8:9], v[2:3], v[106:107]
	v_pk_mul_f32 v[10:11], v[0:1], v[104:105]
	v_cvt_pk_bf16_f32 v3, v6, v7
	v_cvt_pk_bf16_f32 v2, v4, v5
	v_cvt_pk_bf16_f32 v1, v8, v9
	v_cvt_pk_bf16_f32 v0, v10, v11
	ds_write_b128 v222, v[0:3]
	ds_write_b128 v223, v[20:23] offset:59904
.LBB0_706:
	s_or_b64 exec, exec, s[6:7]
	v_lshlrev_b32_e32 v0, 16, v50
	v_and_b32_e32 v1, 0xffff0000, v50
	v_lshlrev_b32_e32 v2, 16, v51
	v_and_b32_e32 v3, 0xffff0000, v51
	s_waitcnt lgkmcnt(0)
	v_pk_mul_f32 v[8:9], v[0:1], v[0:1]
	v_pk_mul_f32 v[10:11], v[2:3], v[2:3]
	v_add_f32_e32 v8, v8, v9
	v_lshlrev_b32_e32 v4, 16, v52
	v_and_b32_e32 v5, 0xffff0000, v52
	v_add_f32_e32 v8, v10, v8
	v_pk_mul_f32 v[12:13], v[4:5], v[4:5]
	v_add_f32_e32 v8, v11, v8
	v_lshlrev_b32_e32 v6, 16, v53
	v_and_b32_e32 v7, 0xffff0000, v53
	v_add_f32_e32 v8, v12, v8
	v_pk_mul_f32 v[14:15], v[6:7], v[6:7]
	v_add_f32_e32 v8, v13, v8
	v_add_f32_e32 v8, v14, v8
	v_add_f32_e32 v8, v15, v8
	s_nop 1
	v_add_f32_dpp v8, v8, v8 quad_perm:[1,0,3,2] row_mask:0xf bank_mask:0xf
	s_nop 1
	v_add_f32_dpp v8, v8, v8 quad_perm:[2,3,0,1] row_mask:0xf bank_mask:0xf
	s_nop 1
	v_add_f32_dpp v8, v8, v8 row_half_mirror row_mask:0xf bank_mask:0xf
	s_and_saveexec_b64 s[6:7], s[94:95]
	s_cbranch_execz .LBB0_708
	v_fmamk_f32 v8, v8, 0x3c800000, v203
	v_rsq_f32_e32 v8, v8
	s_nop 0
	v_pk_mul_f32 v[6:7], v[8:9], v[6:7] op_sel_hi:[0,1]
	v_pk_mul_f32 v[4:5], v[8:9], v[4:5] op_sel_hi:[0,1]
	v_pk_mul_f32 v[2:3], v[8:9], v[2:3] op_sel_hi:[0,1]
	v_pk_mul_f32 v[0:1], v[8:9], v[0:1] op_sel_hi:[0,1]
	v_pk_mul_f32 v[6:7], v[6:7], v[102:103]
	v_pk_mul_f32 v[4:5], v[4:5], v[100:101]
	v_pk_mul_f32 v[8:9], v[2:3], v[106:107]
	v_pk_mul_f32 v[10:11], v[0:1], v[104:105]
	v_cvt_pk_bf16_f32 v3, v6, v7
	v_cvt_pk_bf16_f32 v2, v4, v5
	v_cvt_pk_bf16_f32 v1, v8, v9
	v_cvt_pk_bf16_f32 v0, v10, v11
	ds_write_b128 v224, v[0:3]
	ds_write_b128 v225, v[28:31] offset:59904
.LBB0_708:
	s_or_b64 exec, exec, s[6:7]
	v_lshlrev_b32_e32 v0, 16, v54
	v_and_b32_e32 v1, 0xffff0000, v54
	v_lshlrev_b32_e32 v2, 16, v55
	v_and_b32_e32 v3, 0xffff0000, v55
	s_waitcnt lgkmcnt(0)
	v_pk_mul_f32 v[8:9], v[0:1], v[0:1]
	v_pk_mul_f32 v[10:11], v[2:3], v[2:3]
	v_add_f32_e32 v8, v8, v9
	v_lshlrev_b32_e32 v4, 16, v56
	v_and_b32_e32 v5, 0xffff0000, v56
	v_add_f32_e32 v8, v10, v8
	v_pk_mul_f32 v[12:13], v[4:5], v[4:5]
	v_add_f32_e32 v8, v11, v8
	v_lshlrev_b32_e32 v6, 16, v57
	v_and_b32_e32 v7, 0xffff0000, v57
	v_add_f32_e32 v8, v12, v8
	v_pk_mul_f32 v[14:15], v[6:7], v[6:7]
	v_add_f32_e32 v8, v13, v8
	v_add_f32_e32 v8, v14, v8
	v_add_f32_e32 v8, v15, v8
	s_nop 1
	v_add_f32_dpp v8, v8, v8 quad_perm:[1,0,3,2] row_mask:0xf bank_mask:0xf
	s_nop 1
	v_add_f32_dpp v8, v8, v8 quad_perm:[2,3,0,1] row_mask:0xf bank_mask:0xf
	s_nop 1
	v_add_f32_dpp v8, v8, v8 row_half_mirror row_mask:0xf bank_mask:0xf
	s_and_saveexec_b64 s[6:7], s[8:9]
	s_cbranch_execz .LBB0_710
	v_fmamk_f32 v8, v8, 0x3c800000, v203
	v_rsq_f32_e32 v8, v8
	s_nop 0
	v_pk_mul_f32 v[6:7], v[8:9], v[6:7] op_sel_hi:[0,1]
	v_pk_mul_f32 v[4:5], v[8:9], v[4:5] op_sel_hi:[0,1]
	v_pk_mul_f32 v[2:3], v[8:9], v[2:3] op_sel_hi:[0,1]
	v_pk_mul_f32 v[0:1], v[8:9], v[0:1] op_sel_hi:[0,1]
	v_pk_mul_f32 v[6:7], v[6:7], v[102:103]
	v_pk_mul_f32 v[4:5], v[4:5], v[100:101]
	v_pk_mul_f32 v[8:9], v[2:3], v[106:107]
	v_pk_mul_f32 v[10:11], v[0:1], v[104:105]
	v_cvt_pk_bf16_f32 v3, v6, v7
	v_cvt_pk_bf16_f32 v2, v4, v5
	v_cvt_pk_bf16_f32 v1, v8, v9
	v_cvt_pk_bf16_f32 v0, v10, v11
	ds_write_b128 v226, v[0:3]
	ds_write_b128 v227, v[38:41] offset:59904
